# state items: V^T/decay loads issued before the k_inv gather wait
# speedup vs baseline: 1.0049x; 1.0049x over previous
.LBB0_571:
	v_lshl_add_u64 v[2:3], s[62:63], 0, v[50:51]
	v_lshl_add_u64 v[6:7], s[62:63], 0, v[56:57]
	v_lshl_add_u64 v[8:9], s[62:63], 0, v[60:61]
	v_lshl_add_u64 v[104:105], s[62:63], 0, v[62:63]
	v_lshl_add_u64 v[22:23], s[62:63], 0, v[80:81]
	v_lshl_add_u64 v[32:33], s[62:63], 0, v[38:39]
	v_lshl_add_u64 v[4:5], s[62:63], 0, v[58:59]
	v_lshl_add_u64 v[106:107], s[62:63], 0, v[66:67]
	v_lshl_add_u64 v[110:111], s[62:63], 0, v[68:69]
	v_lshl_add_u64 v[112:113], s[62:63], 0, v[70:71]
	v_lshl_add_u64 v[116:117], s[62:63], 0, v[72:73]
	v_lshl_add_u64 v[114:115], s[62:63], 0, v[74:75]
	v_lshl_add_u64 v[118:119], s[62:63], 0, v[76:77]
	v_lshl_add_u64 v[108:109], s[62:63], 0, v[78:79]
	v_lshl_add_u64 v[14:15], s[62:63], 0, v[42:43]
	v_lshl_add_u64 v[24:25], s[62:63], 0, v[82:83]
	v_lshl_add_u64 v[28:29], s[62:63], 0, v[84:85]
	v_lshl_add_u64 v[98:99], s[62:63], 0, v[86:87]
	v_lshl_add_u64 v[12:13], s[62:63], 0, v[88:89]
	v_lshl_add_u64 v[18:19], s[62:63], 0, v[90:91]
	v_lshl_add_u64 v[10:11], s[62:63], 0, v[92:93]
	v_lshl_add_u64 v[16:17], s[62:63], 0, v[54:55]
	v_lshl_add_u64 v[20:21], s[62:63], 0, v[52:53]
	v_lshl_add_u64 v[26:27], s[62:63], 0, v[48:49]
	v_lshl_add_u64 v[96:97], s[62:63], 0, v[46:47]
	v_lshl_add_u64 v[100:101], s[62:63], 0, v[44:45]
	v_lshl_add_u64 v[30:31], s[62:63], 0, v[40:41]
	global_load_ushort v138, v[104:105], off
	global_load_ushort v142, v[106:107], off
	global_load_ushort v143, v[110:111], off
	global_load_ushort v139, v[112:113], off
	global_load_ushort v157, v[116:117], off
	global_load_ushort v140, v[114:115], off
	global_load_ushort v162, v[118:119], off
	global_load_ushort v141, v[108:109], off
	global_load_ushort v163, v[2:3], off offset:-2048
	global_load_ushort v164, v[2:3], off offset:-1024
	global_load_ushort v165, v[2:3], off
	global_load_ushort v166, v[2:3], off offset:1024
	global_load_ushort v167, v[6:7], off
	s_nop 0
	global_load_ushort v6, v[4:5], off
	global_load_ushort v7, v[8:9], off
	global_load_ushort v168, v[2:3], off offset:-1984
	global_load_ushort v169, v[22:23], off
	global_load_ushort v170, v[14:15], off offset:-1024
	global_load_ushort v171, v[14:15], off
	s_nop 0
	global_load_ushort v22, v[14:15], off offset:1024
	global_load_ushort v23, v[24:25], off
	global_load_ushort v172, v[28:29], off
	global_load_ushort v8, v[98:99], off
	global_load_ushort v9, v[12:13], off
	global_load_ushort v173, v[18:19], off
	global_load_ushort v174, v[10:11], off
	global_load_ushort v175, v[16:17], off
	global_load_ushort v176, v[20:21], off
	global_load_ushort v177, v[26:27], off
	global_load_ushort v178, v[96:97], off
	global_load_ushort v179, v[100:101], off
	global_load_ushort v180, v[30:31], off
	v_add_co_u32_e32 v2, vcc, s11, v32
	v_lshl_add_u64 v[102:103], s[62:63], 0, v[36:37]
	s_nop 0
	v_addc_co_u32_e32 v3, vcc, 0, v33, vcc
	v_add_co_u32_e32 v4, vcc, s12, v102
	v_lshl_add_u64 v[126:127], s[62:63], 0, v[34:35]
	s_nop 0
	v_addc_co_u32_e32 v5, vcc, 0, v103, vcc
	v_add_co_u32_e32 v144, vcc, s14, v126
	v_cvt_pk_bf16_f32 v120, v64, v65
	s_nop 0
	v_addc_co_u32_e32 v145, vcc, 0, v127, vcc
	v_add_co_u32_e32 v146, vcc, s15, v126
	v_cvt_pk_bf16_f32 v121, v94, v95
	s_nop 0
	v_addc_co_u32_e32 v147, vcc, 0, v127, vcc
	v_add_co_u32_e32 v148, vcc, s16, v126
	s_add_i32 s10, s10, -1
	s_nop 0
	v_addc_co_u32_e32 v149, vcc, 0, v127, vcc
	v_add_co_u32_e32 v150, vcc, s17, v126
	v_lshl_add_u64 v[34:35], v[34:35], 0, s[2:3]
	s_nop 0
	v_addc_co_u32_e32 v151, vcc, 0, v127, vcc
	v_add_co_u32_e32 v152, vcc, s18, v126
	v_addc_co_u32_e32 v153, vcc, 0, v127, vcc
	v_add_co_u32_e32 v154, vcc, s19, v126
	s_nop 0
	v_addc_co_u32_e32 v155, vcc, 0, v127, vcc
	v_add_co_u32_e32 v158, vcc, s20, v126
	v_lshl_add_u64 v[36:37], v[36:37], 0, s[4:5]
	s_nop 0
	v_addc_co_u32_e32 v159, vcc, 0, v127, vcc
	v_add_co_u32_e32 v160, vcc, s21, v126
	v_lshl_add_u64 v[38:39], v[38:39], 0, s[6:7]
	s_nop 0
	v_addc_co_u32_e32 v161, vcc, 0, v127, vcc
	global_load_dwordx4 v[18:21], v[2:3], off offset:1024
	global_load_dwordx4 v[96:99], v[2:3], off offset:1056
	global_load_dwordx4 v[100:103], v[4:5], off offset:1024
	global_load_dwordx4 v[104:107], v[4:5], off offset:1280
	global_load_dwordx4 v[108:111], v[4:5], off offset:1536
	global_load_dwordx4 v[112:115], v[4:5], off offset:1792
	global_load_dwordx4 v[116:119], v[4:5], off offset:2048
	global_load_dwordx4 v[126:129], v[4:5], off offset:2304
	global_load_dwordx4 v[130:133], v[4:5], off offset:2560
	global_load_dwordx4 v[134:137], v[4:5], off offset:2816
	s_waitcnt vmcnt(10)
	v_perm_b32 v139, v157, v139, s13
	v_perm_b32 v140, v162, v140, s13
	v_perm_b32 v5, v138, v7, s13
	v_perm_b32 v4, v6, v167, s13
	v_perm_b32 v3, v166, v165, s13
	v_perm_b32 v2, v164, v163, s13
	v_perm_b32 v141, v169, v141, s13
	v_perm_b32 v138, v143, v142, s13
	v_perm_b32 v24, v172, v23, s13
	v_perm_b32 v23, v22, v171, s13
	v_perm_b32 v22, v170, v168, s13
	s_waitcnt lgkmcnt(0)
	s_barrier
	v_perm_b32 v25, v9, v8, s13
	s_waitcnt vmcnt(9)
	v_mfma_f32_32x32x16_bf16 v[2:17], v[2:5], v[18:21], 0
	v_perm_b32 v143, v180, v179, s13
	v_perm_b32 v142, v178, v177, s13
	v_lshl_add_u64 v[40:41], v[40:41], 0, s[8:9]
	v_lshl_add_u64 v[42:43], v[42:43], 0, s[8:9]
	v_lshl_add_u64 v[44:45], v[44:45], 0, s[8:9]
	v_lshl_add_u64 v[46:47], v[46:47], 0, s[8:9]
	v_lshl_add_u64 v[48:49], v[48:49], 0, s[8:9]
	v_mfma_f32_32x32x16_bf16 v[18:33], v[22:25], v[18:21], 0
	v_lshl_add_u64 v[50:51], v[50:51], 0, s[8:9]
	v_lshl_add_u64 v[52:53], v[52:53], 0, s[8:9]
	v_lshl_add_u64 v[54:55], v[54:55], 0, s[8:9]
	v_lshl_add_u64 v[56:57], v[56:57], 0, s[8:9]
	v_lshl_add_u64 v[58:59], v[58:59], 0, s[8:9]
	v_lshl_add_u64 v[60:61], v[60:61], 0, s[8:9]
	v_lshl_add_u64 v[62:63], v[62:63], 0, s[8:9]
	s_waitcnt vmcnt(8)
	v_mfma_f32_32x32x16_bf16 v[2:17], v[138:141], v[96:99], v[2:17]
	v_perm_b32 v141, v176, v175, s13
	v_perm_b32 v140, v174, v173, s13
	v_lshl_add_u64 v[66:67], v[66:67], 0, s[8:9]
	v_lshl_add_u64 v[68:69], v[68:69], 0, s[8:9]
	v_lshl_add_u64 v[70:71], v[70:71], 0, s[8:9]
	v_lshl_add_u64 v[72:73], v[72:73], 0, s[8:9]
	v_lshl_add_u64 v[74:75], v[74:75], 0, s[8:9]
	v_mfma_f32_32x32x16_bf16 v[18:33], v[140:143], v[96:99], v[18:33]
	s_nop 3
	ds_write_b128 v1, v[2:5]
	ds_write_b128 v1, v[6:9] offset:32
	ds_write_b128 v1, v[10:13] offset:64
	ds_write_b128 v1, v[14:17] offset:96
	s_nop 3
	ds_write_b128 v1, v[18:21] offset:128
	ds_write_b128 v1, v[22:25] offset:160
	ds_write_b128 v1, v[26:29] offset:192
	ds_write_b128 v1, v[30:33] offset:224
	s_waitcnt lgkmcnt(0)
	s_barrier
	global_store_dwordx2 v[144:145], v[120:121], off offset:1024
	ds_read_b128 v[2:5], v125
	ds_read_b128 v[6:9], v125 offset:8704
	ds_read_b128 v[10:13], v125 offset:17408
	ds_read_b128 v[14:17], v125 offset:26112
	ds_read_b128 v[18:21], v125 offset:34816
	ds_read_b128 v[22:25], v125 offset:43520
	ds_read_b128 v[26:29], v125 offset:52224
	ds_read_b128 v[30:33], v125 offset:60928
	s_waitcnt lgkmcnt(7)
	v_pk_add_f32 v[2:3], v[64:65], v[2:3]
	v_pk_add_f32 v[4:5], v[94:95], v[4:5]
	s_waitcnt vmcnt(8)
	v_pk_mul_f32 v[94:95], v[100:101], v[2:3]
	v_pk_mul_f32 v[64:65], v[102:103], v[4:5]
	s_waitcnt lgkmcnt(6)
	v_pk_fma_f32 v[2:3], v[100:101], v[2:3], v[6:7]
	v_pk_fma_f32 v[4:5], v[102:103], v[4:5], v[8:9]
	v_cvt_pk_bf16_f32 v6, v94, v95
	v_cvt_pk_bf16_f32 v7, v64, v65
	s_waitcnt vmcnt(7)
	v_pk_mul_f32 v[8:9], v[106:107], v[4:5]
	v_pk_mul_f32 v[64:65], v[104:105], v[2:3]
	s_waitcnt lgkmcnt(5)
	v_pk_fma_f32 v[4:5], v[106:107], v[4:5], v[12:13]
	v_pk_fma_f32 v[2:3], v[104:105], v[2:3], v[10:11]
	global_store_dwordx2 v[146:147], v[6:7], off offset:1024
	v_cvt_pk_bf16_f32 v6, v64, v65
	v_cvt_pk_bf16_f32 v7, v8, v9
	s_waitcnt vmcnt(7)
	v_pk_mul_f32 v[8:9], v[110:111], v[4:5]
	v_pk_mul_f32 v[10:11], v[108:109], v[2:3]
	s_waitcnt lgkmcnt(4)
	v_pk_fma_f32 v[4:5], v[110:111], v[4:5], v[16:17]
	v_pk_fma_f32 v[2:3], v[108:109], v[2:3], v[14:15]
	global_store_dwordx2 v[148:149], v[6:7], off offset:1024
	v_cvt_pk_bf16_f32 v6, v10, v11
	v_cvt_pk_bf16_f32 v7, v8, v9
	s_waitcnt vmcnt(7)
	v_pk_mul_f32 v[8:9], v[114:115], v[4:5]
	v_pk_mul_f32 v[10:11], v[112:113], v[2:3]
	s_waitcnt lgkmcnt(3)
	v_pk_fma_f32 v[4:5], v[114:115], v[4:5], v[20:21]
	v_pk_fma_f32 v[2:3], v[112:113], v[2:3], v[18:19]
	global_store_dwordx2 v[150:151], v[6:7], off offset:1024
	v_cvt_pk_bf16_f32 v6, v10, v11
	v_cvt_pk_bf16_f32 v7, v8, v9
	s_waitcnt vmcnt(7)
	v_pk_mul_f32 v[8:9], v[118:119], v[4:5]
	v_pk_mul_f32 v[10:11], v[116:117], v[2:3]
	s_waitcnt lgkmcnt(2)
	v_pk_fma_f32 v[4:5], v[118:119], v[4:5], v[24:25]
	v_pk_fma_f32 v[2:3], v[116:117], v[2:3], v[22:23]
	global_store_dwordx2 v[152:153], v[6:7], off offset:1024
	v_cvt_pk_bf16_f32 v6, v10, v11
	v_cvt_pk_bf16_f32 v7, v8, v9
	s_waitcnt vmcnt(7)
	v_pk_mul_f32 v[8:9], v[128:129], v[4:5]
	v_pk_mul_f32 v[10:11], v[126:127], v[2:3]
	s_waitcnt lgkmcnt(1)
	v_pk_fma_f32 v[4:5], v[128:129], v[4:5], v[28:29]
	v_pk_fma_f32 v[2:3], v[126:127], v[2:3], v[26:27]
	global_store_dwordx2 v[154:155], v[6:7], off offset:1024
	v_cvt_pk_bf16_f32 v6, v10, v11
	v_cvt_pk_bf16_f32 v7, v8, v9
	s_waitcnt vmcnt(7)
	v_pk_mul_f32 v[8:9], v[132:133], v[4:5]
	v_pk_mul_f32 v[10:11], v[130:131], v[2:3]
	s_waitcnt lgkmcnt(0)
	v_pk_fma_f32 v[4:5], v[132:133], v[4:5], v[32:33]
	v_pk_fma_f32 v[2:3], v[130:131], v[2:3], v[30:31]
	v_lshl_add_u64 v[76:77], v[76:77], 0, s[8:9]
	v_lshl_add_u64 v[78:79], v[78:79], 0, s[8:9]
	v_lshl_add_u64 v[80:81], v[80:81], 0, s[8:9]
	v_lshl_add_u64 v[82:83], v[82:83], 0, s[8:9]
	v_lshl_add_u64 v[84:85], v[84:85], 0, s[8:9]
	v_lshl_add_u64 v[86:87], v[86:87], 0, s[8:9]
	v_lshl_add_u64 v[88:89], v[88:89], 0, s[8:9]
	v_lshl_add_u64 v[90:91], v[90:91], 0, s[8:9]
	v_lshl_add_u64 v[92:93], v[92:93], 0, s[8:9]
	s_cmp_eq_u32 s10, 0
	global_store_dwordx2 v[158:159], v[6:7], off offset:1024
	v_cvt_pk_bf16_f32 v6, v10, v11
	v_cvt_pk_bf16_f32 v7, v8, v9
	s_waitcnt vmcnt(7)
	v_pk_mul_f32 v[94:95], v[136:137], v[4:5]
	v_pk_mul_f32 v[64:65], v[134:135], v[2:3]
	global_store_dwordx2 v[160:161], v[6:7], off offset:1024
	s_cbranch_scc0 .LBB0_571
	s_waitcnt vmcnt(0)
	s_barrier
	s_and_saveexec_b64 s[2:3], s[44:45]
	s_cbranch_execz .LBB0_576
	s_mov_b64 s[4:5], exec
	buffer_wbl2 sc1
	s_waitcnt vmcnt(0)
	s_waitcnt vmcnt(0)
	v_mbcnt_lo_u32_b32 v1, s4, 0
	v_mbcnt_hi_u32_b32 v1, s5, v1
	v_cmp_eq_u32_e32 vcc, 0, v1
	s_and_saveexec_b64 s[6:7], vcc
	s_cbranch_execz .LBB0_575
	s_lshl_b64 s[0:1], s[0:1], 2
	s_add_u32 s0, s46, s0
	s_addc_u32 s1, s47, s1
	s_bcnt1_i32_b64 s4, s[4:5]
	v_mov_b32_e32 v1, 0
	v_mov_b32_e32 v2, s4
	global_atomic_add v1, v2, s[0:1]
	global_atomic_add v1, v2, s[46:47] offset:256
